# in-proj A side job's x-row loads issued inside the K-loop (iterations 3/4, into quads the store trickle has vacated), copied to v198-213 at K-loop exit; on top of v64
# baseline (speedup 1.0000x reference)
;     __device__ __forceinline__ void side_issue(Side& s, int ui, int c, int wid, int lane) const {
;         s.row = (c * upc + ui) * 8 + wid;
.Lpka_nomove:
	s_mov_b32 s100, 0
	s_add_i32 s32, s27, s43
	s_lshl_b32 s32, s32, 3
	s_add_i32 s32, s32, s14
	s_cmp_lt_i32 s32, s95
	s_cselect_b32 s32, s32, -1

; #define PG8_WAIT_V(n) asm volatile("s_waitcnt vmcnt(" #n ")" ::: "memory")
; #define PG8_WAIT_L(n) asm volatile("s_waitcnt lgkmcnt(" #n ")" ::: "memory")
; #define PG8_BAR __builtin_amdgcn_s_barrier()
; #define PG8_SCHED __builtin_amdgcn_sched_barrier(0)
;     ...
;             PG8_WAIT_V(8); PG8_WAIT_L(0); PG8_BAR; PG8_MMA(0, 0, At, B0); PG8_MMA(0, 1, At, B1); PG8_BAR; PG8_SCHED;
.Lpka_na:
	s_bcnt1_i32_b32 vcc_lo, s100
	s_cmp_eq_u32 vcc_lo, 0
	s_cbranch_scc1 .Lpka_w8a
	s_cmp_eq_u32 vcc_lo, 1
	s_cbranch_scc1 .Lpka_w9a
	s_cmp_eq_u32 vcc_lo, 2
	s_cbranch_scc1 .Lpka_w10a
	s_waitcnt vmcnt(11)
	s_branch .Lpka_da
.Lpka_w10a:
	s_waitcnt vmcnt(10)
	s_branch .Lpka_da

; #define PG8_STAGE(bufoff, gbase, voff) do { _Pragma("unroll") for (int _i = 0; _i < 2; ++_i) \
;         __builtin_amdgcn_global_load_lds((const unsigned*)((const char*)(gbase) + (voff)[_i]), (PG8_LAS unsigned*)(lds + (bufoff) + ldsw + _i * 8192), 16, 0, 0); } while (0)
; #define PG8_LDA(dst, b, h) do { _Pragma("unroll") for (int m = 0; m < 4; ++m) _Pragma("unroll") for (int k = 0; k < 2; ++k) dst[m][k] = *(const PG8_LAS bf16x8*)(lds + PG8_SA(b, h) + aoff + m * 2048 + k * 1024); } while (0)
; #define PG8_WAIT_V(n) asm volatile("s_waitcnt vmcnt(" #n ")" ::: "memory")
; #define PG8_WAIT_L(n) asm volatile("s_waitcnt lgkmcnt(" #n ")" ::: "memory")
; #define PG8_BAR __builtin_amdgcn_s_barrier()
; #define PG8_SCHED __builtin_amdgcn_sched_barrier(0)
;     __device__ __forceinline__ void side_issue(Side& s, int ui, int c, int wid, int lane) const {
;     ...
;         if (MODE == 0 && s.row < xrows) { const f32x4* xr = (const f32x4*)(xs + (size_t)s.row * 1024) + lane;
; #pragma unroll
;             for (int j = 0; j < 4; ++j) s.v[j] = __builtin_nontemporal_load(xr + 64 * j); }
;     ...
;             PG8_WAIT_V(8); PG8_WAIT_L(0); PG8_BAR; PG8_MMA(0, 0, At, B0); PG8_MMA(0, 1, At, B1); PG8_BAR; PG8_SCHED;
;             PG8_LDA(At, 0, 1); PG8_STAGE(PG8_SB(0, 0), b2, voffB); PG8_STAGE(PG8_SB(0, 1), b2 + hstepB, voffB); PG8_STAGE(PG8_SA(0, 0), a2, voffA);
.Lpka_da:
	s_waitcnt lgkmcnt(0)
	s_barrier
	s_setprio 1
	s_waitcnt lgkmcnt(0)
	v_mfma_f32_16x16x32_bf16 v[132:135], v[144:147], v[210:213], v[132:135]
	v_mfma_f32_16x16x32_bf16 v[128:131], v[152:155], v[210:213], v[128:131]
	v_mfma_f32_16x16x32_bf16 v[116:119], v[144:147], v[218:221], v[116:119]
	v_mfma_f32_16x16x32_bf16 v[112:115], v[152:155], v[218:221], v[112:115]
	v_mfma_f32_16x16x32_bf16 v[100:103], v[144:147], v[226:229], v[100:103]
	v_mfma_f32_16x16x32_bf16 v[96:99], v[152:155], v[226:229], v[96:99]
	v_mfma_f32_16x16x32_bf16 v[84:87], v[144:147], v[234:237], v[84:87]
	v_mfma_f32_16x16x32_bf16 v[80:83], v[152:155], v[234:237], v[80:83]
	v_mfma_f32_16x16x32_bf16 v[132:135], v[148:151], v[214:217], v[132:135]
	v_mfma_f32_16x16x32_bf16 v[128:131], v[156:159], v[214:217], v[128:131]
	v_mfma_f32_16x16x32_bf16 v[116:119], v[148:151], v[222:225], v[116:119]
	v_mfma_f32_16x16x32_bf16 v[112:115], v[156:159], v[222:225], v[112:115]
	v_mfma_f32_16x16x32_bf16 v[100:103], v[148:151], v[230:233], v[100:103]
	v_mfma_f32_16x16x32_bf16 v[96:99], v[156:159], v[230:233], v[96:99]
	v_mfma_f32_16x16x32_bf16 v[84:87], v[148:151], v[238:241], v[84:87]
	v_mfma_f32_16x16x32_bf16 v[80:83], v[156:159], v[238:241], v[80:83]
	s_setprio 0
	s_setprio 1
	v_mfma_f32_16x16x32_bf16 v[140:143], v[186:189], v[210:213], v[140:143]
	v_mfma_f32_16x16x32_bf16 v[136:139], v[202:205], v[210:213], v[136:139]
	v_mfma_f32_16x16x32_bf16 v[124:127], v[186:189], v[218:221], v[124:127]
	v_mfma_f32_16x16x32_bf16 v[120:123], v[202:205], v[218:221], v[120:123]
	v_mfma_f32_16x16x32_bf16 v[108:111], v[186:189], v[226:229], v[108:111]
	v_mfma_f32_16x16x32_bf16 v[104:107], v[202:205], v[226:229], v[104:107]
	v_mfma_f32_16x16x32_bf16 v[92:95], v[186:189], v[234:237], v[92:95]
	v_mfma_f32_16x16x32_bf16 v[88:91], v[202:205], v[234:237], v[88:91]
	v_mfma_f32_16x16x32_bf16 v[140:143], v[198:201], v[214:217], v[140:143]
	v_mfma_f32_16x16x32_bf16 v[136:139], v[206:209], v[214:217], v[136:139]
	v_mfma_f32_16x16x32_bf16 v[124:127], v[198:201], v[222:225], v[124:127]
	v_mfma_f32_16x16x32_bf16 v[120:123], v[206:209], v[222:225], v[120:123]
	v_mfma_f32_16x16x32_bf16 v[108:111], v[198:201], v[230:233], v[108:111]
	v_mfma_f32_16x16x32_bf16 v[104:107], v[206:209], v[230:233], v[104:107]
	v_mfma_f32_16x16x32_bf16 v[92:95], v[198:201], v[238:241], v[92:95]
	v_mfma_f32_16x16x32_bf16 v[88:91], v[206:209], v[238:241], v[88:91]
	s_setprio 0
	s_barrier
	s_add_i32 s82, s82, s15
	s_mov_b32 m0, s82
	ds_read_b128 v[210:213], v197 offset:16384
	ds_read_b128 v[214:217], v197 offset:17408
	ds_read_b128 v[218:221], v197 offset:18432
	ds_read_b128 v[222:225], v197 offset:19456
	ds_read_b128 v[226:229], v197 offset:20480
	ds_read_b128 v[230:233], v197 offset:21504
	ds_read_b128 v[234:237], v197 offset:22528
	ds_read_b128 v[238:241], v197 offset:23552
	global_load_lds_dwordx4 v170, s[72:73]
	s_add_i32 m0, s82, 0x2000
	s_add_u32 s82, s72, 0x10000
	s_addc_u32 s83, s73, 0
	s_add_i32 s86, s86, s15
	global_load_lds_dwordx4 v166, s[72:73]
	s_mov_b32 m0, s86
	s_nop 0
	global_load_lds_dwordx4 v170, s[82:83]
	s_add_i32 m0, s86, 0x2000
	s_nop 0
	global_load_lds_dwordx4 v166, s[82:83]
	s_mov_b32 m0, s63
	s_nop 0
	global_load_lds_dwordx4 v172, s[76:77]
	s_mov_b32 m0, s64
	s_nop 0
	global_load_lds_dwordx4 v168, s[76:77]
	s_lshl_b32 s100, s100, 1
	s_and_b32 s100, s100, 6
	s_cmp_lt_i32 s32, 0
	s_cbranch_scc1 .Lsl_nb
	s_cmp_eq_u32 s81, 4
	s_cbranch_scc1 .Lsl_xb
	s_cmp_eq_u32 s81, 6
	s_cbranch_scc0 .Lsl_nb
	s_or_b32 s100, s100, 1
	s_lshl_b32 vcc_lo, s32, 12
	s_mov_b32 vcc_hi, 0
	v_lshl_add_u64 v[242:243], v[174:175], 0, vcc
	global_load_dwordx4 v[162:165], v[242:243], off offset:2048 nt
	s_branch .Lsl_nb
.Lsl_xb:
	s_or_b32 s100, s100, 1
	s_lshl_b32 vcc_lo, s32, 12
	s_mov_b32 vcc_hi, 0
	v_lshl_add_u64 v[242:243], v[174:175], 0, vcc
	global_load_dwordx4 v[244:247], v[242:243], off nt

; #define PG8_STAGE(bufoff, gbase, voff) do { _Pragma("unroll") for (int _i = 0; _i < 2; ++_i) \
;         __builtin_amdgcn_global_load_lds((const unsigned*)((const char*)(gbase) + (voff)[_i]), (PG8_LAS unsigned*)(lds + (bufoff) + ldsw + _i * 8192), 16, 0, 0); } while (0)
; #define PG8_LDA(dst, b, h) do { _Pragma("unroll") for (int m = 0; m < 4; ++m) _Pragma("unroll") for (int k = 0; k < 2; ++k) dst[m][k] = *(const PG8_LAS bf16x8*)(lds + PG8_SA(b, h) + aoff + m * 2048 + k * 1024); } while (0)
; #define PG8_WAIT_V(n) asm volatile("s_waitcnt vmcnt(" #n ")" ::: "memory")
; #define PG8_WAIT_L(n) asm volatile("s_waitcnt lgkmcnt(" #n ")" ::: "memory")
; #define PG8_BAR __builtin_amdgcn_s_barrier()
; #define PG8_SCHED __builtin_amdgcn_sched_barrier(0)
;     __device__ __forceinline__ void side_issue(Side& s, int ui, int c, int wid, int lane) const {
;     ...
;         if (MODE == 0 && s.row < xrows) { const f32x4* xr = (const f32x4*)(xs + (size_t)s.row * 1024) + lane;
; #pragma unroll
;             for (int j = 0; j < 4; ++j) s.v[j] = __builtin_nontemporal_load(xr + 64 * j); }
;     ...
;             PG8_WAIT_V(8); PG8_WAIT_L(0); PG8_BAR; PG8_MMA(0, 0, At, B0); PG8_MMA(0, 1, At, B1); PG8_BAR; PG8_SCHED;
;             PG8_LDA(At, 1, 1); PG8_STAGE(PG8_SB(1, 0), b3, voffB); PG8_STAGE(PG8_SB(1, 1), b3 + hstepB, voffB); PG8_STAGE(PG8_SA(1, 0), a3, voffA);
.Lpka_dc:
	s_waitcnt lgkmcnt(0)
	s_barrier
	s_setprio 1
	s_waitcnt lgkmcnt(0)
	v_mfma_f32_16x16x32_bf16 v[132:135], v[144:147], v[210:213], v[132:135]
	v_mfma_f32_16x16x32_bf16 v[128:131], v[152:155], v[210:213], v[128:131]
	v_mfma_f32_16x16x32_bf16 v[116:119], v[144:147], v[218:221], v[116:119]
	v_mfma_f32_16x16x32_bf16 v[112:115], v[152:155], v[218:221], v[112:115]
	v_mfma_f32_16x16x32_bf16 v[100:103], v[144:147], v[226:229], v[100:103]
	v_mfma_f32_16x16x32_bf16 v[96:99], v[152:155], v[226:229], v[96:99]
	v_mfma_f32_16x16x32_bf16 v[84:87], v[144:147], v[234:237], v[84:87]
	v_mfma_f32_16x16x32_bf16 v[80:83], v[152:155], v[234:237], v[80:83]
	v_mfma_f32_16x16x32_bf16 v[132:135], v[148:151], v[214:217], v[132:135]
	v_mfma_f32_16x16x32_bf16 v[128:131], v[156:159], v[214:217], v[128:131]
	v_mfma_f32_16x16x32_bf16 v[116:119], v[148:151], v[222:225], v[116:119]
	v_mfma_f32_16x16x32_bf16 v[112:115], v[156:159], v[222:225], v[112:115]
	v_mfma_f32_16x16x32_bf16 v[100:103], v[148:151], v[230:233], v[100:103]
	v_mfma_f32_16x16x32_bf16 v[96:99], v[156:159], v[230:233], v[96:99]
	v_mfma_f32_16x16x32_bf16 v[84:87], v[148:151], v[238:241], v[84:87]
	v_mfma_f32_16x16x32_bf16 v[80:83], v[156:159], v[238:241], v[80:83]
	s_setprio 0
	s_setprio 1
	v_mfma_f32_16x16x32_bf16 v[140:143], v[186:189], v[210:213], v[140:143]
	v_mfma_f32_16x16x32_bf16 v[136:139], v[202:205], v[210:213], v[136:139]
	v_mfma_f32_16x16x32_bf16 v[124:127], v[186:189], v[218:221], v[124:127]
	v_mfma_f32_16x16x32_bf16 v[120:123], v[202:205], v[218:221], v[120:123]
	v_mfma_f32_16x16x32_bf16 v[108:111], v[186:189], v[226:229], v[108:111]
	v_mfma_f32_16x16x32_bf16 v[104:107], v[202:205], v[226:229], v[104:107]
	v_mfma_f32_16x16x32_bf16 v[92:95], v[186:189], v[234:237], v[92:95]
	v_mfma_f32_16x16x32_bf16 v[88:91], v[202:205], v[234:237], v[88:91]
	v_mfma_f32_16x16x32_bf16 v[140:143], v[198:201], v[214:217], v[140:143]
	v_mfma_f32_16x16x32_bf16 v[136:139], v[206:209], v[214:217], v[136:139]
	v_mfma_f32_16x16x32_bf16 v[124:127], v[198:201], v[222:225], v[124:127]
	v_mfma_f32_16x16x32_bf16 v[120:123], v[206:209], v[222:225], v[120:123]
	v_mfma_f32_16x16x32_bf16 v[108:111], v[198:201], v[230:233], v[108:111]
	v_mfma_f32_16x16x32_bf16 v[104:107], v[206:209], v[230:233], v[104:107]
	v_mfma_f32_16x16x32_bf16 v[92:95], v[198:201], v[238:241], v[92:95]
	v_mfma_f32_16x16x32_bf16 v[88:91], v[206:209], v[238:241], v[88:91]
	s_setprio 0
	s_barrier
	s_add_i32 m0, s82, s15
	s_add_u32 vcc_lo, s72, 0x80
	s_addc_u32 vcc_hi, s73, 0
	ds_read_b128 v[210:213], v197 offset:49152
	ds_read_b128 v[214:217], v197 offset:50176
	ds_read_b128 v[218:221], v197 offset:51200
	ds_read_b128 v[222:225], v197 offset:52224
	ds_read_b128 v[226:229], v197 offset:53248
	ds_read_b128 v[230:233], v197 offset:54272
	ds_read_b128 v[234:237], v197 offset:55296
	ds_read_b128 v[238:241], v197 offset:56320
	global_load_lds_dwordx4 v170, vcc
	s_add_i32 m0, m0, 0x2000
	s_nop 0
	global_load_lds_dwordx4 v166, vcc
	s_add_u32 s72, s72, 0x10080
	s_addc_u32 s73, s73, 0
	s_add_i32 m0, s83, s15
	s_nop 0
	global_load_lds_dwordx4 v170, s[72:73]
	s_add_i32 m0, m0, 0x2000
	s_nop 0
	global_load_lds_dwordx4 v166, s[72:73]
	s_add_u32 vcc_lo, s76, 0xfffc0080
	s_addc_u32 vcc_hi, s77, -1
	s_mov_b32 m0, s74
	s_nop 0
	global_load_lds_dwordx4 v172, vcc
	s_mov_b32 m0, s75
	s_nop 0
	global_load_lds_dwordx4 v168, vcc
	s_lshl_b32 s100, s100, 1
	s_and_b32 s100, s100, 6
	s_cmp_lt_i32 s32, 0
	s_cbranch_scc1 .Lsl_ne
	s_cmp_eq_u32 s81, 4
	s_cbranch_scc1 .Lsl_xe
	s_cmp_eq_u32 s81, 6
	s_cbranch_scc0 .Lsl_ne
	s_or_b32 s100, s100, 1
	s_lshl_b32 vcc_lo, s32, 12
	s_mov_b32 vcc_hi, 0
	v_lshl_add_u64 v[242:243], v[174:175], 0, vcc
	global_load_dwordx4 v[190:193], v[242:243], off offset:3072 nt
	s_branch .Lsl_ne
.Lsl_xe:
	s_or_b32 s100, s100, 1
	s_lshl_b32 vcc_lo, s32, 12
	s_mov_b32 vcc_hi, 0
	v_lshl_add_u64 v[242:243], v[174:175], 0, vcc
	global_load_dwordx4 v[248:251], v[242:243], off offset:1024 nt

; #define PG8_WAIT_V(n) asm volatile("s_waitcnt vmcnt(" #n ")" ::: "memory")
; #define PG8_WAIT_L(n) asm volatile("s_waitcnt lgkmcnt(" #n ")" ::: "memory")
; #define PG8_BAR __builtin_amdgcn_s_barrier()
; #define PG8_SCHED __builtin_amdgcn_sched_barrier(0)
;     ...
;             PG8_WAIT_V(8); PG8_WAIT_L(0); PG8_BAR; PG8_MMA(1, 0, At, B0); PG8_MMA(1, 1, At, B1); PG8_BAR; PG8_SCHED;
;         }
;         if constexpr (ALIGN_EPI) { if (wr == 0) PG8_BAR; }
;         if (war_cnt && ui == 0) { unsigned sp_ = 0; while (__hip_atomic_load(war_cnt, __ATOMIC_RELAXED, __HIP_MEMORY_SCOPE_AGENT) < war_need && ++sp_ < (1u << 22)) __builtin_amdgcn_s_sleep(2); }
;         typename Epi::Side side_; E.side_issue(side_, ui, S.c, wid, lane);
.Lpka_de:
	s_waitcnt lgkmcnt(0)
	s_barrier
	s_setprio 1
	s_waitcnt lgkmcnt(0)
	v_mfma_f32_16x16x32_bf16 v[68:71], v[144:147], v[210:213], v[68:71]
	v_mfma_f32_16x16x32_bf16 v[64:67], v[152:155], v[210:213], v[64:67]
	v_mfma_f32_16x16x32_bf16 v[52:55], v[144:147], v[218:221], v[52:55]
	v_mfma_f32_16x16x32_bf16 v[48:51], v[152:155], v[218:221], v[48:51]
	v_mfma_f32_16x16x32_bf16 v[36:39], v[144:147], v[226:229], v[36:39]
	v_mfma_f32_16x16x32_bf16 v[32:35], v[152:155], v[226:229], v[32:35]
	v_mfma_f32_16x16x32_bf16 v[20:23], v[144:147], v[234:237], v[20:23]
	v_mfma_f32_16x16x32_bf16 v[16:19], v[152:155], v[234:237], v[16:19]
	v_mfma_f32_16x16x32_bf16 v[68:71], v[148:151], v[214:217], v[68:71]
	v_mfma_f32_16x16x32_bf16 v[64:67], v[156:159], v[214:217], v[64:67]
	v_mfma_f32_16x16x32_bf16 v[52:55], v[148:151], v[222:225], v[52:55]
	v_mfma_f32_16x16x32_bf16 v[48:51], v[156:159], v[222:225], v[48:51]
	v_mfma_f32_16x16x32_bf16 v[36:39], v[148:151], v[230:233], v[36:39]
	v_mfma_f32_16x16x32_bf16 v[32:35], v[156:159], v[230:233], v[32:35]
	v_mfma_f32_16x16x32_bf16 v[20:23], v[148:151], v[238:241], v[20:23]
	v_mfma_f32_16x16x32_bf16 v[16:19], v[156:159], v[238:241], v[16:19]
	s_setprio 0
	s_setprio 1
	v_mfma_f32_16x16x32_bf16 v[76:79], v[186:189], v[210:213], v[76:79]
	v_mfma_f32_16x16x32_bf16 v[72:75], v[202:205], v[210:213], v[72:75]
	v_mfma_f32_16x16x32_bf16 v[60:63], v[186:189], v[218:221], v[60:63]
	v_mfma_f32_16x16x32_bf16 v[56:59], v[202:205], v[218:221], v[56:59]
	v_mfma_f32_16x16x32_bf16 v[44:47], v[186:189], v[226:229], v[44:47]
	v_mfma_f32_16x16x32_bf16 v[40:43], v[202:205], v[226:229], v[40:43]
	v_mfma_f32_16x16x32_bf16 v[24:27], v[186:189], v[234:237], v[24:27]
	v_mfma_f32_16x16x32_bf16 v[28:31], v[202:205], v[234:237], v[28:31]
	v_mfma_f32_16x16x32_bf16 v[76:79], v[198:201], v[214:217], v[76:79]
	v_mfma_f32_16x16x32_bf16 v[72:75], v[206:209], v[214:217], v[72:75]
	v_mfma_f32_16x16x32_bf16 v[60:63], v[198:201], v[222:225], v[60:63]
	v_mfma_f32_16x16x32_bf16 v[56:59], v[206:209], v[222:225], v[56:59]
	v_mfma_f32_16x16x32_bf16 v[44:47], v[198:201], v[230:233], v[44:47]
	v_mfma_f32_16x16x32_bf16 v[40:43], v[206:209], v[230:233], v[40:43]
	v_mfma_f32_16x16x32_bf16 v[24:27], v[198:201], v[238:241], v[24:27]
	v_mfma_f32_16x16x32_bf16 v[28:31], v[206:209], v[238:241], v[28:31]
	s_setprio 0
	s_barrier
	s_add_i32 s81, s81, 2
	s_add_u32 s38, s38, 0x100
	s_addc_u32 s39, s39, 0
	s_add_u32 s61, s61, 0x100
	s_addc_u32 s80, s80, 0
	s_cmp_gt_u32 s81, 13
	s_cbranch_scc0 .LBB0_206
	v_mov_b32_e32 v210, v244
	v_mov_b32_e32 v211, v245
	v_mov_b32_e32 v212, v246
	v_mov_b32_e32 v213, v247
	v_mov_b32_e32 v206, v248
	v_mov_b32_e32 v207, v249
	v_mov_b32_e32 v208, v250
	v_mov_b32_e32 v209, v251
	v_mov_b32_e32 v202, v162
	v_mov_b32_e32 v203, v163
	v_mov_b32_e32 v204, v164
	v_mov_b32_e32 v205, v165
	v_mov_b32_e32 v198, v190
	v_mov_b32_e32 v199, v191
	v_mov_b32_e32 v200, v192
	v_mov_b32_e32 v201, v193
	v_mov_b32_e32 v162, 0x500
	v_mov_b32_e32 v163, 0
	v_mov_b32_e32 v164, 0x4ff
	v_mov_b32_e32 v165, 0
	v_mov_b32_e32 v190, 0x358637bd
	v_mov_b32_e32 v191, 1
	v_mov_b32_e32 v192, 0x300
	v_mov_b32_e32 v193, 0x200
	s_and_b64 vcc, exec, s[22:23]
	s_cbranch_vccz .LBB0_209
	s_barrier

;     __device__ __forceinline__ void side_issue(Side& s, int ui, int c, int wid, int lane) const {
;         s.row = (c * upc + ui) * 8 + wid;
;     __device__ __forceinline__ void operator()(const f32x4 (&acc)[2][2][4][2], const Unit& u, int wr, int wc, int fr, int fq, const bool reuse, PG8_LAS float* rscr, PG8_LAS const float* gains) const {
;         const int sec = u.pn >> 2, hq = u.pn & 3, h = hq * 4 + wc;
;         int type, g = 0;
;         if (MODE == 0) { if (sec == 9) type = 3; else { g = sec / 3; type = sec - 3 * g; } } else type = sec;
.LBB0_221:
	s_add_i32 s2, s27, s43
	s_lshl_b32 s2, s2, 3
	s_add_i32 s76, s2, s14
	s_cmp_lt_i32 s76, s95
	s_cselect_b64 s[80:81], -1, 0
	s_cmp_ge_i32 s76, s95
	s_cbranch_scc1 .LBB0_223
	s_ashr_i32 s77, s76, 31
	s_lshl_b64 s[38:39], s[76:77], 12
.LBB0_223:
	s_ashr_i32 s38, s13, 2
	s_cmp_eq_u32 s38, 9
	s_cbranch_scc1 .LBB0_225
	s_mul_hi_i32 s2, s38, 0x55555556
	s_lshr_b32 s27, s2, 31
	s_add_i32 s2, s2, s27
	s_mul_i32 s27, s2, -3
	s_add_i32 s27, s27, s38
	s_branch .LBB0_226
